# GEMM bodies: first K-loop iteration peeled with MFMA SrcC=0 on each accumulator's first use; the 128-instruction per-unit accumulator clear deleted
# speedup vs baseline: 1.0089x; 1.0089x over previous
; #define PG8_STAGE(bufoff, gbase, voff) do { _Pragma("unroll") for (int _i = 0; _i < 2; ++_i) \
;         __builtin_amdgcn_global_load_lds((const unsigned*)((const char*)(gbase) + (voff)[_i]), (PG8_LAS unsigned*)(lds + (bufoff) + ldsw + _i * 8192), 16, 0, 0); } while (0)
; #define PG8_LDA(dst, b, h) do { _Pragma("unroll") for (int m = 0; m < 4; ++m) _Pragma("unroll") for (int k = 0; k < 2; ++k) dst[m][k] = *(const PG8_LAS bf16x8*)(lds + PG8_SA(b, h) + aoff + m * 2048 + k * 1024); } while (0)
; #define PG8_LDB(dst, b, h) do { _Pragma("unroll") for (int n = 0; n < 2; ++n) _Pragma("unroll") for (int k = 0; k < 2; ++k) dst[n][k] = *(const PG8_LAS bf16x8*)(lds + PG8_SB(b, h) + boff + n * 2048 + k * 1024); } while (0)
; #define PG8_MMA(ai, bj, At, Bt) do { __builtin_amdgcn_s_setprio(1); _Pragma("unroll") for (int m = 0; m < 4; ++m) _Pragma("unroll") for (int n = 0; n < 2; ++n) _Pragma("unroll") for (int k = 0; k < 2; ++k) \
;         acc[ai][bj][m][n] = __builtin_amdgcn_mfma_f32_16x16x32_bf16(Bt[n][k], At[m][k], acc[ai][bj][m][n], 0, 0, 0); __builtin_amdgcn_s_setprio(0); } while (0)
; template <class Epi, class Sched, bool ALIGN_EPI = false, bool SP2 = false>
; __device__ __forceinline__ void gemm_phase(PG8_LAS unsigned char* lds, const Gemm g, const Sched& S, const Epi& E, int tid_in) {
;     ...
;             const bool last = (t == ntc - 2);
;             const char* a1 = PG8_KA(cA, t + 1);
;             const char* a2 = last ? nA : PG8_KA(cA, t + 2); const char* b2 = last ? nB : cB + (size_t)(t + 2) * kstep;
;             const char* a3 = last ? PG8_KA(nA, 1) : PG8_KA(cA, t + 3); const char* b3 = b2 + kstep;
;             if (last && has_next) S.a_ready(nxt);
;             if constexpr (SP2) {
;             PG8_LDB(B0, 0, 0); PG8_LDB(B1, 0, 1); PG8_SCHED; PG8_LDA(At, 0, 0); PG8_STAGE(PG8_SA(1, 1), a1 + hstepA, voffA);
;             PG8_WAIT_V(8); PG8_WAIT_L(0); PG8_BAR; PG8_MMA(0, 0, At, B0); PG8_MMA(0, 1, At, B1); PG8_BAR; PG8_SCHED;
;             PG8_LDA(At, 0, 1); PG8_STAGE(PG8_SB(0, 0), b2, voffB); PG8_STAGE(PG8_SB(0, 1), b2 + hstep, voffB); PG8_STAGE(PG8_SA(0, 0), a2, voffA);
;     ...
;         for (int a = 0; a < 2; ++a)
; #pragma unroll
;             for (int b = 0; b < 2; ++b)
; #pragma unroll
;                 for (int m = 0; m < 4; ++m)
; #pragma unroll
;                     for (int n = 0; n < 2; ++n) acc[a][b][m][n] = (f32x4){0.f, 0.f, 0.f, 0.f};
.LBB0_605:
	s_add_u32 s18, s40, 0x80
	s_addc_u32 s19, s41, 0
	s_add_u32 s20, s10, 0x100
	s_addc_u32 s21, s11, 0
	s_add_u32 s0, s2, 0x80
	s_addc_u32 s1, s3, 0
	s_waitcnt lgkmcnt(0)
	v_lshl_add_u64 v[130:131], s[0:1], 0, v[206:207]
	v_lshl_add_u64 v[132:133], s[0:1], 0, v[208:209]
	s_lshl_b64 s[0:1], s[94:95], 7
	s_add_u32 s22, s0, 0xffffff00
	s_mov_b32 s10, 0
	s_mov_b64 s[0:1], 0
	s_waitcnt vmcnt(0)
	s_or_b32 s11, s10, 1
	s_cmp_ge_u32 s11, s84
	s_cselect_b32 s27, s86, 0
	s_cselect_b32 s79, s85, 0
	s_add_i32 s23, s10, 2
	s_cmp_ge_u32 s23, s84
	s_cselect_b32 s44, s86, 0
	s_cselect_b32 s11, s85, 0
	s_add_u32 s44, s44, s0
	s_addc_u32 s11, s11, s1
	s_add_u32 s44, s2, s44
	s_addc_u32 s11, s3, s11
	s_add_u32 s44, s44, 0x100
	s_addc_u32 s11, s11, 0
	s_add_u32 s46, s20, s0
	s_addc_u32 s47, s21, s1
	s_add_i32 s10, s10, 3
	s_cmp_ge_u32 s10, s84
	s_cselect_b32 s45, s86, 0
	s_cselect_b32 s10, s85, 0
	s_add_u32 s45, s45, s0
	s_addc_u32 s10, s10, s1
	s_add_u32 s45, s2, s45
	s_addc_u32 s10, s3, s10
	s_add_u32 s78, s45, 0x180
	s_addc_u32 s10, s10, 0
	s_cmp_eq_u32 s22, s0
	s_cselect_b32 s45, s41, s11
	s_cselect_b32 s44, s40, s44
	s_cselect_b32 s47, s43, s47
	s_cselect_b32 s46, s42, s46
	s_cselect_b32 s11, s19, s10
	s_cselect_b32 s10, s18, s78
	s_add_i32 s81, 0, 0x10000
	v_add_u32_e32 v0, s81, v205
	s_add_i32 s82, 0, 0x14000
	ds_read_b128 v[134:137], v0
	ds_read_b128 v[138:141], v0 offset:1024
	ds_read_b128 v[142:145], v0 offset:2048
	ds_read_b128 v[146:149], v0 offset:3072
	v_add_u32_e32 v0, s82, v205
	ds_read_b128 v[150:153], v0
	ds_read_b128 v[154:157], v0 offset:1024
	ds_read_b128 v[158:161], v0 offset:2048
	ds_read_b128 v[162:165], v0 offset:3072
	s_add_u32 s78, s27, s0
	s_addc_u32 s79, s79, s1
	v_lshl_add_u64 v[214:215], v[130:131], 0, s[78:79]
	s_add_i32 m0, s58, 0xc000
	ds_read_b128 v[166:169], v246
	ds_read_b128 v[170:173], v246 offset:1024
	ds_read_b128 v[174:177], v246 offset:2048
	ds_read_b128 v[178:181], v246 offset:3072
	ds_read_b128 v[182:185], v246 offset:4096
	ds_read_b128 v[186:189], v246 offset:5120
	ds_read_b128 v[190:193], v246 offset:6144
	ds_read_b128 v[210:213], v246 offset:7168
	global_load_lds_dwordx4 v[214:215], off
	v_lshl_add_u64 v[214:215], v[132:133], 0, s[78:79]
	s_add_i32 m0, s58, 0xe000
	s_nop 0
	global_load_lds_dwordx4 v[214:215], off
	s_waitcnt vmcnt(8)
	s_waitcnt lgkmcnt(0)
	s_barrier
	s_setprio 1
	s_waitcnt lgkmcnt(0)
	v_mfma_f32_16x16x32_bf16 v[122:125], v[134:137], v[166:169], 0
	v_mfma_f32_16x16x32_bf16 v[114:117], v[142:145], v[166:169], 0
	v_mfma_f32_16x16x32_bf16 v[106:109], v[134:137], v[174:177], 0
	v_mfma_f32_16x16x32_bf16 v[98:101], v[142:145], v[174:177], 0
	v_mfma_f32_16x16x32_bf16 v[90:93], v[134:137], v[182:185], 0
	v_mfma_f32_16x16x32_bf16 v[82:85], v[142:145], v[182:185], 0
	v_mfma_f32_16x16x32_bf16 v[74:77], v[134:137], v[190:193], 0
	v_mfma_f32_16x16x32_bf16 v[66:69], v[142:145], v[190:193], 0
	v_mfma_f32_16x16x32_bf16 v[122:125], v[138:141], v[170:173], v[122:125]
	v_mfma_f32_16x16x32_bf16 v[114:117], v[146:149], v[170:173], v[114:117]
	v_mfma_f32_16x16x32_bf16 v[106:109], v[138:141], v[178:181], v[106:109]
	v_mfma_f32_16x16x32_bf16 v[98:101], v[146:149], v[178:181], v[98:101]
	v_mfma_f32_16x16x32_bf16 v[90:93], v[138:141], v[186:189], v[90:93]
	v_mfma_f32_16x16x32_bf16 v[82:85], v[146:149], v[186:189], v[82:85]
	v_mfma_f32_16x16x32_bf16 v[74:77], v[138:141], v[210:213], v[74:77]
	v_mfma_f32_16x16x32_bf16 v[66:69], v[146:149], v[210:213], v[66:69]
	s_setprio 0
	s_setprio 1
	v_mfma_f32_16x16x32_bf16 v[126:129], v[150:153], v[166:169], 0
	v_mfma_f32_16x16x32_bf16 v[118:121], v[158:161], v[166:169], 0
	v_mfma_f32_16x16x32_bf16 v[110:113], v[150:153], v[174:177], 0
	v_mfma_f32_16x16x32_bf16 v[102:105], v[158:161], v[174:177], 0
	v_mfma_f32_16x16x32_bf16 v[94:97], v[150:153], v[182:185], 0
	v_mfma_f32_16x16x32_bf16 v[86:89], v[158:161], v[182:185], 0
	v_mfma_f32_16x16x32_bf16 v[78:81], v[150:153], v[190:193], 0
	v_mfma_f32_16x16x32_bf16 v[70:73], v[158:161], v[190:193], 0
	v_mfma_f32_16x16x32_bf16 v[126:129], v[154:157], v[170:173], v[126:129]
	v_mfma_f32_16x16x32_bf16 v[118:121], v[162:165], v[170:173], v[118:121]
	v_mfma_f32_16x16x32_bf16 v[110:113], v[154:157], v[178:181], v[110:113]
	v_mfma_f32_16x16x32_bf16 v[102:105], v[162:165], v[178:181], v[102:105]
	v_mfma_f32_16x16x32_bf16 v[94:97], v[154:157], v[186:189], v[94:97]
	v_mfma_f32_16x16x32_bf16 v[86:89], v[162:165], v[186:189], v[86:89]
	v_mfma_f32_16x16x32_bf16 v[78:81], v[154:157], v[210:213], v[78:81]
	v_mfma_f32_16x16x32_bf16 v[70:73], v[162:165], v[210:213], v[70:73]
	s_setprio 0
	s_barrier
	s_add_i32 s27, s81, s55
	v_lshl_add_u64 v[214:215], s[46:47], 0, v[202:203]
	s_mov_b32 m0, s27
	ds_read_b128 v[166:169], v246 offset:16384
	ds_read_b128 v[170:173], v246 offset:17408
	ds_read_b128 v[174:177], v246 offset:18432
	ds_read_b128 v[178:181], v246 offset:19456
	ds_read_b128 v[182:185], v246 offset:20480
	ds_read_b128 v[186:189], v246 offset:21504
	ds_read_b128 v[190:193], v246 offset:22528
	ds_read_b128 v[210:213], v246 offset:23552
	global_load_lds_dwordx4 v[214:215], off
	s_add_i32 m0, s27, 0x2000
	v_lshl_add_u64 v[216:217], s[46:47], 0, v[198:199]
	s_add_u32 s46, s46, s52
	s_addc_u32 s47, s47, 0
	s_add_i32 s27, s82, s55
	global_load_lds_dwordx4 v[216:217], off
	v_lshl_add_u64 v[218:219], s[46:47], 0, v[202:203]
	s_mov_b32 m0, s27
	v_lshl_add_u64 v[220:221], s[46:47], 0, v[198:199]
	global_load_lds_dwordx4 v[218:219], off
	s_add_i32 m0, s27, 0x2000
	v_lshl_add_u64 v[234:235], s[44:45], 0, v[200:201]
	global_load_lds_dwordx4 v[220:221], off
	s_mov_b32 m0, s58
	s_nop 0
	global_load_lds_dwordx4 v[234:235], off
	v_lshl_add_u64 v[234:235], s[44:45], 0, v[196:197]
	s_mov_b32 m0, s59
	s_nop 0
	global_load_lds_dwordx4 v[234:235], off
	s_waitcnt vmcnt(8)
	s_waitcnt lgkmcnt(0)
	s_barrier
; #define PG8_STAGE(bufoff, gbase, voff) do { _Pragma("unroll") for (int _i = 0; _i < 2; ++_i) \
;         __builtin_amdgcn_global_load_lds((const unsigned*)((const char*)(gbase) + (voff)[_i]), (PG8_LAS unsigned*)(lds + (bufoff) + ldsw + _i * 8192), 16, 0, 0); } while (0)
; #define PG8_LDA(dst, b, h) do { _Pragma("unroll") for (int m = 0; m < 4; ++m) _Pragma("unroll") for (int k = 0; k < 2; ++k) dst[m][k] = *(const PG8_LAS bf16x8*)(lds + PG8_SA(b, h) + aoff + m * 2048 + k * 1024); } while (0)
; #define PG8_LDB(dst, b, h) do { _Pragma("unroll") for (int n = 0; n < 2; ++n) _Pragma("unroll") for (int k = 0; k < 2; ++k) dst[n][k] = *(const PG8_LAS bf16x8*)(lds + PG8_SB(b, h) + boff + n * 2048 + k * 1024); } while (0)
; #define PG8_MMA(ai, bj, At, Bt) do { __builtin_amdgcn_s_setprio(1); _Pragma("unroll") for (int m = 0; m < 4; ++m) _Pragma("unroll") for (int n = 0; n < 2; ++n) _Pragma("unroll") for (int k = 0; k < 2; ++k) \
;         acc[ai][bj][m][n] = __builtin_amdgcn_mfma_f32_16x16x32_bf16(Bt[n][k], At[m][k], acc[ai][bj][m][n], 0, 0, 0); __builtin_amdgcn_s_setprio(0); } while (0)
; #define PG8_WAIT_V(n) asm volatile("s_waitcnt vmcnt(" #n ")" ::: "memory")
; #define PG8_WAIT_L(n) asm volatile("s_waitcnt lgkmcnt(" #n ")" ::: "memory")
; #define PG8_BAR __builtin_amdgcn_s_barrier()
; #define PG8_SCHED __builtin_amdgcn_sched_barrier(0)
; template <class Epi, class Sched, bool ALIGN_EPI = false, bool SP2 = false>
; __device__ __forceinline__ void gemm_phase(PG8_LAS unsigned char* lds, const Gemm g, const Sched& S, const Epi& E, int tid_in) {
;     ...
;             PG8_WAIT_V(8); PG8_WAIT_L(0); PG8_BAR; PG8_MMA(1, 0, At, B0); PG8_MMA(1, 1, At, B1); PG8_BAR; PG8_SCHED;
;             PG8_LDB(B0, 1, 0); PG8_LDB(B1, 1, 1); PG8_SCHED; PG8_LDA(At, 1, 0); PG8_STAGE(PG8_SA(0, 1), a2 + hstepA, voffA);
;             PG8_WAIT_V(8); PG8_WAIT_L(0); PG8_BAR; PG8_MMA(0, 0, At, B0); PG8_MMA(0, 1, At, B1); PG8_BAR; PG8_SCHED;
	s_setprio 1
	s_waitcnt lgkmcnt(0)
	v_mfma_f32_16x16x32_bf16 v[58:61], v[134:137], v[166:169], 0
	v_mfma_f32_16x16x32_bf16 v[50:53], v[142:145], v[166:169], 0
	v_mfma_f32_16x16x32_bf16 v[42:45], v[134:137], v[174:177], 0
	v_mfma_f32_16x16x32_bf16 v[34:37], v[142:145], v[174:177], 0
	v_mfma_f32_16x16x32_bf16 v[26:29], v[134:137], v[182:185], 0
	v_mfma_f32_16x16x32_bf16 v[18:21], v[142:145], v[182:185], 0
	v_mfma_f32_16x16x32_bf16 v[10:13], v[134:137], v[190:193], 0
	v_mfma_f32_16x16x32_bf16 v[6:9], v[142:145], v[190:193], 0
	v_mfma_f32_16x16x32_bf16 v[58:61], v[138:141], v[170:173], v[58:61]
	v_mfma_f32_16x16x32_bf16 v[50:53], v[146:149], v[170:173], v[50:53]
	v_mfma_f32_16x16x32_bf16 v[42:45], v[138:141], v[178:181], v[42:45]
	v_mfma_f32_16x16x32_bf16 v[34:37], v[146:149], v[178:181], v[34:37]
	v_mfma_f32_16x16x32_bf16 v[26:29], v[138:141], v[186:189], v[26:29]
	v_mfma_f32_16x16x32_bf16 v[18:21], v[146:149], v[186:189], v[18:21]
	v_mfma_f32_16x16x32_bf16 v[10:13], v[138:141], v[210:213], v[10:13]
	v_mfma_f32_16x16x32_bf16 v[6:9], v[146:149], v[210:213], v[6:9]
	s_setprio 0
	s_setprio 1
	v_mfma_f32_16x16x32_bf16 v[62:65], v[150:153], v[166:169], 0
	v_mfma_f32_16x16x32_bf16 v[54:57], v[158:161], v[166:169], 0
	v_mfma_f32_16x16x32_bf16 v[46:49], v[150:153], v[174:177], 0
	v_mfma_f32_16x16x32_bf16 v[38:41], v[158:161], v[174:177], 0
	v_mfma_f32_16x16x32_bf16 v[30:33], v[150:153], v[182:185], 0
	v_mfma_f32_16x16x32_bf16 v[22:25], v[158:161], v[182:185], 0
	v_mfma_f32_16x16x32_bf16 v[14:17], v[150:153], v[190:193], 0
	v_mfma_f32_16x16x32_bf16 v[2:5], v[158:161], v[190:193], 0
	v_mfma_f32_16x16x32_bf16 v[62:65], v[154:157], v[170:173], v[62:65]
	v_mfma_f32_16x16x32_bf16 v[54:57], v[162:165], v[170:173], v[54:57]
	v_mfma_f32_16x16x32_bf16 v[46:49], v[154:157], v[178:181], v[46:49]
	v_mfma_f32_16x16x32_bf16 v[38:41], v[162:165], v[178:181], v[38:41]
	v_mfma_f32_16x16x32_bf16 v[30:33], v[154:157], v[186:189], v[30:33]
	v_mfma_f32_16x16x32_bf16 v[22:25], v[162:165], v[186:189], v[22:25]
	v_mfma_f32_16x16x32_bf16 v[14:17], v[154:157], v[210:213], v[14:17]
	v_mfma_f32_16x16x32_bf16 v[2:5], v[162:165], v[210:213], v[2:5]
	s_setprio 0
	s_barrier
	s_add_i32 s27, 0, 0x18000
	v_add_u32_e32 v0, s27, v205
	s_add_i32 s46, 0, 0x1c000
	ds_read_b128 v[134:137], v0
	ds_read_b128 v[138:141], v0 offset:1024
	ds_read_b128 v[142:145], v0 offset:2048
	ds_read_b128 v[146:149], v0 offset:3072
	v_add_u32_e32 v0, s46, v205
	ds_read_b128 v[150:153], v0
	ds_read_b128 v[154:157], v0 offset:1024
	ds_read_b128 v[158:161], v0 offset:2048
	ds_read_b128 v[162:165], v0 offset:3072
	s_add_u32 s44, s44, s28
	s_addc_u32 s45, s45, 0
	s_mov_b32 m0, s60
	v_lshl_add_u64 v[234:235], s[44:45], 0, v[200:201]
	ds_read_b128 v[166:169], v246 offset:32768
	ds_read_b128 v[170:173], v246 offset:33792
	ds_read_b128 v[174:177], v246 offset:34816
	ds_read_b128 v[178:181], v246 offset:35840
	ds_read_b128 v[182:185], v246 offset:36864
	ds_read_b128 v[186:189], v246 offset:37888
	ds_read_b128 v[190:193], v246 offset:38912
	ds_read_b128 v[210:213], v246 offset:39936
	global_load_lds_dwordx4 v[234:235], off
	v_lshl_add_u64 v[234:235], s[44:45], 0, v[196:197]
	s_mov_b32 m0, s61
	s_nop 0
	global_load_lds_dwordx4 v[234:235], off
	s_waitcnt vmcnt(8)
	s_waitcnt lgkmcnt(0)
	s_barrier
	s_setprio 1
	s_waitcnt lgkmcnt(0)
	v_mfma_f32_16x16x32_bf16 v[122:125], v[134:137], v[166:169], v[122:125]
	v_mfma_f32_16x16x32_bf16 v[114:117], v[142:145], v[166:169], v[114:117]
	v_mfma_f32_16x16x32_bf16 v[106:109], v[134:137], v[174:177], v[106:109]
	v_mfma_f32_16x16x32_bf16 v[98:101], v[142:145], v[174:177], v[98:101]
	v_mfma_f32_16x16x32_bf16 v[90:93], v[134:137], v[182:185], v[90:93]
	v_mfma_f32_16x16x32_bf16 v[82:85], v[142:145], v[182:185], v[82:85]
	v_mfma_f32_16x16x32_bf16 v[74:77], v[134:137], v[190:193], v[74:77]
	v_mfma_f32_16x16x32_bf16 v[66:69], v[142:145], v[190:193], v[66:69]
	v_mfma_f32_16x16x32_bf16 v[122:125], v[138:141], v[170:173], v[122:125]
	v_mfma_f32_16x16x32_bf16 v[114:117], v[146:149], v[170:173], v[114:117]
	v_mfma_f32_16x16x32_bf16 v[106:109], v[138:141], v[178:181], v[106:109]
	v_mfma_f32_16x16x32_bf16 v[98:101], v[146:149], v[178:181], v[98:101]
	v_mfma_f32_16x16x32_bf16 v[90:93], v[138:141], v[186:189], v[90:93]
	v_mfma_f32_16x16x32_bf16 v[82:85], v[146:149], v[186:189], v[82:85]
	v_mfma_f32_16x16x32_bf16 v[74:77], v[138:141], v[210:213], v[74:77]
	v_mfma_f32_16x16x32_bf16 v[66:69], v[146:149], v[210:213], v[66:69]
	s_setprio 0
	s_setprio 1
	v_mfma_f32_16x16x32_bf16 v[126:129], v[150:153], v[166:169], v[126:129]
	v_mfma_f32_16x16x32_bf16 v[118:121], v[158:161], v[166:169], v[118:121]
	v_mfma_f32_16x16x32_bf16 v[110:113], v[150:153], v[174:177], v[110:113]
	v_mfma_f32_16x16x32_bf16 v[102:105], v[158:161], v[174:177], v[102:105]
	v_mfma_f32_16x16x32_bf16 v[94:97], v[150:153], v[182:185], v[94:97]
	v_mfma_f32_16x16x32_bf16 v[86:89], v[158:161], v[182:185], v[86:89]
	v_mfma_f32_16x16x32_bf16 v[78:81], v[150:153], v[190:193], v[78:81]
	v_mfma_f32_16x16x32_bf16 v[70:73], v[158:161], v[190:193], v[70:73]
	v_mfma_f32_16x16x32_bf16 v[126:129], v[154:157], v[170:173], v[126:129]
	v_mfma_f32_16x16x32_bf16 v[118:121], v[162:165], v[170:173], v[118:121]
	v_mfma_f32_16x16x32_bf16 v[110:113], v[154:157], v[178:181], v[110:113]
	v_mfma_f32_16x16x32_bf16 v[102:105], v[162:165], v[178:181], v[102:105]
	v_mfma_f32_16x16x32_bf16 v[94:97], v[154:157], v[186:189], v[94:97]
	v_mfma_f32_16x16x32_bf16 v[86:89], v[162:165], v[186:189], v[86:89]
	v_mfma_f32_16x16x32_bf16 v[78:81], v[154:157], v[210:213], v[78:81]
	v_mfma_f32_16x16x32_bf16 v[70:73], v[162:165], v[210:213], v[70:73]
	s_setprio 0
	s_barrier
; #define PG8_STAGE(bufoff, gbase, voff) do { _Pragma("unroll") for (int _i = 0; _i < 2; ++_i) \
;         __builtin_amdgcn_global_load_lds((const unsigned*)((const char*)(gbase) + (voff)[_i]), (PG8_LAS unsigned*)(lds + (bufoff) + ldsw + _i * 8192), 16, 0, 0); } while (0)
; #define PG8_LDA(dst, b, h) do { _Pragma("unroll") for (int m = 0; m < 4; ++m) _Pragma("unroll") for (int k = 0; k < 2; ++k) dst[m][k] = *(const PG8_LAS bf16x8*)(lds + PG8_SA(b, h) + aoff + m * 2048 + k * 1024); } while (0)
; #define PG8_MMA(ai, bj, At, Bt) do { __builtin_amdgcn_s_setprio(1); _Pragma("unroll") for (int m = 0; m < 4; ++m) _Pragma("unroll") for (int n = 0; n < 2; ++n) _Pragma("unroll") for (int k = 0; k < 2; ++k) \
;         acc[ai][bj][m][n] = __builtin_amdgcn_mfma_f32_16x16x32_bf16(Bt[n][k], At[m][k], acc[ai][bj][m][n], 0, 0, 0); __builtin_amdgcn_s_setprio(0); } while (0)
; #define PG8_WAIT_V(n) asm volatile("s_waitcnt vmcnt(" #n ")" ::: "memory")
; #define PG8_WAIT_L(n) asm volatile("s_waitcnt lgkmcnt(" #n ")" ::: "memory")
; #define PG8_BAR __builtin_amdgcn_s_barrier()
; #define PG8_SCHED __builtin_amdgcn_sched_barrier(0)
; template <class Epi, class Sched, bool ALIGN_EPI = false, bool SP2 = false>
; __device__ __forceinline__ void gemm_phase(PG8_LAS unsigned char* lds, const Gemm g, const Sched& S, const Epi& E, int tid_in) {
;     ...
;             PG8_LDA(At, 1, 1); PG8_STAGE(PG8_SB(1, 0), b3, voffB); PG8_STAGE(PG8_SB(1, 1), b3 + hstep, voffB); PG8_STAGE(PG8_SA(1, 0), a3, voffA);
;             PG8_WAIT_V(8); PG8_WAIT_L(0); PG8_BAR; PG8_MMA(1, 0, At, B0); PG8_MMA(1, 1, At, B1); PG8_BAR; PG8_SCHED;
	s_add_i32 s27, s27, s55
	v_lshl_add_u64 v[214:215], v[214:215], 0, s[96:97]
	s_mov_b32 m0, s27
	ds_read_b128 v[166:169], v246 offset:49152
	ds_read_b128 v[170:173], v246 offset:50176
	ds_read_b128 v[174:177], v246 offset:51200
	ds_read_b128 v[178:181], v246 offset:52224
	ds_read_b128 v[182:185], v246 offset:53248
	ds_read_b128 v[186:189], v246 offset:54272
	ds_read_b128 v[190:193], v246 offset:55296
	ds_read_b128 v[210:213], v246 offset:56320
	global_load_lds_dwordx4 v[214:215], off
	v_lshl_add_u64 v[214:215], v[216:217], 0, s[96:97]
	s_add_i32 m0, s27, 0x2000
	s_add_i32 s27, s46, s55
	global_load_lds_dwordx4 v[214:215], off
	v_lshl_add_u64 v[214:215], v[218:219], 0, s[96:97]
	s_mov_b32 m0, s27
	s_nop 0
	global_load_lds_dwordx4 v[214:215], off
	v_lshl_add_u64 v[214:215], v[220:221], 0, s[96:97]
	s_add_i32 m0, s27, 0x2000
	s_nop 0
	global_load_lds_dwordx4 v[214:215], off
	v_lshl_add_u64 v[214:215], s[10:11], 0, v[200:201]
	s_mov_b32 m0, s63
	s_nop 0
	global_load_lds_dwordx4 v[214:215], off
	v_lshl_add_u64 v[214:215], s[10:11], 0, v[196:197]
	s_mov_b32 m0, s64
	s_nop 0
	global_load_lds_dwordx4 v[214:215], off
	s_waitcnt vmcnt(8)
	s_waitcnt lgkmcnt(0)
	s_barrier
	s_setprio 1
	s_waitcnt lgkmcnt(0)
	v_mfma_f32_16x16x32_bf16 v[58:61], v[134:137], v[166:169], v[58:61]
	v_mfma_f32_16x16x32_bf16 v[50:53], v[142:145], v[166:169], v[50:53]
	v_mfma_f32_16x16x32_bf16 v[42:45], v[134:137], v[174:177], v[42:45]
	v_mfma_f32_16x16x32_bf16 v[34:37], v[142:145], v[174:177], v[34:37]
	v_mfma_f32_16x16x32_bf16 v[26:29], v[134:137], v[182:185], v[26:29]
	v_mfma_f32_16x16x32_bf16 v[18:21], v[142:145], v[182:185], v[18:21]
	v_mfma_f32_16x16x32_bf16 v[10:13], v[134:137], v[190:193], v[10:13]
	v_mfma_f32_16x16x32_bf16 v[6:9], v[142:145], v[190:193], v[6:9]
	v_mfma_f32_16x16x32_bf16 v[58:61], v[138:141], v[170:173], v[58:61]
	v_mfma_f32_16x16x32_bf16 v[50:53], v[146:149], v[170:173], v[50:53]
	v_mfma_f32_16x16x32_bf16 v[42:45], v[138:141], v[178:181], v[42:45]
	v_mfma_f32_16x16x32_bf16 v[34:37], v[146:149], v[178:181], v[34:37]
	v_mfma_f32_16x16x32_bf16 v[26:29], v[138:141], v[186:189], v[26:29]
	v_mfma_f32_16x16x32_bf16 v[18:21], v[146:149], v[186:189], v[18:21]
	v_mfma_f32_16x16x32_bf16 v[10:13], v[138:141], v[210:213], v[10:13]
	v_mfma_f32_16x16x32_bf16 v[6:9], v[146:149], v[210:213], v[6:9]
	s_setprio 0
	s_setprio 1
	v_mfma_f32_16x16x32_bf16 v[62:65], v[150:153], v[166:169], v[62:65]
	v_mfma_f32_16x16x32_bf16 v[54:57], v[158:161], v[166:169], v[54:57]
	v_mfma_f32_16x16x32_bf16 v[46:49], v[150:153], v[174:177], v[46:49]
	v_mfma_f32_16x16x32_bf16 v[38:41], v[158:161], v[174:177], v[38:41]
	v_mfma_f32_16x16x32_bf16 v[30:33], v[150:153], v[182:185], v[30:33]
	v_mfma_f32_16x16x32_bf16 v[22:25], v[158:161], v[182:185], v[22:25]
	v_mfma_f32_16x16x32_bf16 v[14:17], v[150:153], v[190:193], v[14:17]
	v_mfma_f32_16x16x32_bf16 v[2:5], v[158:161], v[190:193], v[2:5]
	v_mfma_f32_16x16x32_bf16 v[62:65], v[154:157], v[170:173], v[62:65]
	v_mfma_f32_16x16x32_bf16 v[54:57], v[162:165], v[170:173], v[54:57]
	v_mfma_f32_16x16x32_bf16 v[46:49], v[154:157], v[178:181], v[46:49]
	v_mfma_f32_16x16x32_bf16 v[38:41], v[162:165], v[178:181], v[38:41]
	v_mfma_f32_16x16x32_bf16 v[30:33], v[154:157], v[186:189], v[30:33]
	v_mfma_f32_16x16x32_bf16 v[22:25], v[162:165], v[186:189], v[22:25]
	v_mfma_f32_16x16x32_bf16 v[14:17], v[154:157], v[210:213], v[14:17]
	v_mfma_f32_16x16x32_bf16 v[2:5], v[162:165], v[210:213], v[2:5]
	s_setprio 0
	s_barrier
	s_add_u32 s0, s0, 0x100
	s_addc_u32 s1, s1, 0
	s_cmp_ge_u32 s23, s94
	s_mov_b32 s10, s23
	s_cbranch_scc1 .Lzk0_exit

; #define PG8_STAGE(bufoff, gbase, voff) do { _Pragma("unroll") for (int _i = 0; _i < 2; ++_i) \
;         __builtin_amdgcn_global_load_lds((const unsigned*)((const char*)(gbase) + (voff)[_i]), (PG8_LAS unsigned*)(lds + (bufoff) + ldsw + _i * 8192), 16, 0, 0); } while (0)
; #define PG8_LDA(dst, b, h) do { _Pragma("unroll") for (int m = 0; m < 4; ++m) _Pragma("unroll") for (int k = 0; k < 2; ++k) dst[m][k] = *(const PG8_LAS bf16x8*)(lds + PG8_SA(b, h) + aoff + m * 2048 + k * 1024); } while (0)
; #define PG8_LDB(dst, b, h) do { _Pragma("unroll") for (int n = 0; n < 2; ++n) _Pragma("unroll") for (int k = 0; k < 2; ++k) dst[n][k] = *(const PG8_LAS bf16x8*)(lds + PG8_SB(b, h) + boff + n * 2048 + k * 1024); } while (0)
; #define PG8_MMA(ai, bj, At, Bt) do { __builtin_amdgcn_s_setprio(1); _Pragma("unroll") for (int m = 0; m < 4; ++m) _Pragma("unroll") for (int n = 0; n < 2; ++n) _Pragma("unroll") for (int k = 0; k < 2; ++k) \
;         acc[ai][bj][m][n] = __builtin_amdgcn_mfma_f32_16x16x32_bf16(Bt[n][k], At[m][k], acc[ai][bj][m][n], 0, 0, 0); __builtin_amdgcn_s_setprio(0); } while (0)
; template <class Epi, class Sched, bool ALIGN_EPI = false, bool SP2 = false>
; __device__ __forceinline__ void gemm_phase(PG8_LAS unsigned char* lds, const Gemm g, const Sched& S, const Epi& E, int tid_in) {
;     ...
;             const bool last = (t == ntc - 2);
;             const char* a1 = PG8_KA(cA, t + 1);
;             const char* a2 = last ? nA : PG8_KA(cA, t + 2); const char* b2 = last ? nB : cB + (size_t)(t + 2) * kstep;
;             const char* a3 = last ? PG8_KA(nA, 1) : PG8_KA(cA, t + 3); const char* b3 = b2 + kstep;
;             if (last && has_next) S.a_ready(nxt);
;             if constexpr (SP2) {
;             PG8_LDB(B0, 0, 0); PG8_LDB(B1, 0, 1); PG8_SCHED; PG8_LDA(At, 0, 0); PG8_STAGE(PG8_SA(1, 1), a1 + hstepA, voffA);
;             PG8_WAIT_V(8); PG8_WAIT_L(0); PG8_BAR; PG8_MMA(0, 0, At, B0); PG8_MMA(0, 1, At, B1); PG8_BAR; PG8_SCHED;
;             PG8_LDA(At, 0, 1); PG8_STAGE(PG8_SB(0, 0), b2, voffB); PG8_STAGE(PG8_SB(0, 1), b2 + hstep, voffB); PG8_STAGE(PG8_SA(0, 0), a2, voffA);
;     ...
;         for (int a = 0; a < 2; ++a)
; #pragma unroll
;             for (int b = 0; b < 2; ++b)
; #pragma unroll
;                 for (int m = 0; m < 4; ++m)
; #pragma unroll
;                     for (int n = 0; n < 2; ++n) acc[a][b][m][n] = (f32x4){0.f, 0.f, 0.f, 0.f};
.LBB0_1179:
	s_add_u32 s21, s48, 0x80
	s_addc_u32 s53, s49, 0
	s_add_u32 s54, s8, 0x100
	s_addc_u32 s55, s9, 0
	s_mov_b32 s0, 0
	s_mov_b32 s56, s79
	s_waitcnt vmcnt(0)
	s_or_b32 s1, s0, 1
	s_cmp_ge_u32 s1, s84
	s_cselect_b32 s58, s86, 0
	s_cselect_b32 s59, s85, 0
	s_add_i32 s57, s0, 2
	s_cmp_ge_u32 s57, s84
	s_cselect_b32 s8, s86, 0
	s_cselect_b32 s1, s85, 0
	s_add_u32 s8, s6, s8
	s_addc_u32 s1, s7, s1
	s_add_u32 s8, s8, 0x100
	s_addc_u32 s1, s1, 0
	s_add_i32 s0, s0, 3
	s_cmp_ge_u32 s0, s84
	s_cselect_b32 s9, s86, 0
	s_cselect_b32 s0, s85, 0
	s_add_u32 s9, s6, s9
	s_addc_u32 s0, s7, s0
	s_add_u32 s62, s9, 0x180
	s_addc_u32 s0, s0, 0
	s_cmp_eq_u32 s56, 0
	s_cselect_b32 s9, s49, s1
	s_cselect_b32 s8, s48, s8
	s_cselect_b32 s61, s51, s55
	s_cselect_b32 s60, s50, s54
	s_cselect_b32 s1, s53, s0
	s_cselect_b32 s0, s21, s62
	s_add_i32 s62, 0, 0x10000
	v_add_u32_e32 v0, s62, v207
	s_add_i32 s63, 0, 0x14000
	ds_read_b128 v[132:135], v0
	ds_read_b128 v[136:139], v0 offset:1024
	ds_read_b128 v[140:143], v0 offset:2048
	ds_read_b128 v[144:147], v0 offset:3072
	v_add_u32_e32 v0, s63, v207
	ds_read_b128 v[148:151], v0
	ds_read_b128 v[152:155], v0 offset:1024
	ds_read_b128 v[156:159], v0 offset:2048
	ds_read_b128 v[160:163], v0 offset:3072
	v_lshl_add_u64 v[2:3], s[6:7], 0, v[180:181]
	v_lshl_add_u64 v[2:3], v[2:3], 0, s[58:59]
	s_add_i32 m0, s89, 0xc000
	ds_read_b128 v[164:167], v208
	ds_read_b128 v[168:171], v208 offset:1024
	ds_read_b128 v[184:187], v208 offset:2048
	ds_read_b128 v[188:191], v208 offset:3072
	ds_read_b128 v[196:199], v208 offset:4096
	ds_read_b128 v[200:203], v208 offset:5120
	ds_read_b128 v[210:213], v208 offset:6144
	ds_read_b128 v[214:217], v208 offset:7168
	global_load_lds_dwordx4 v[2:3], off
	v_lshl_add_u64 v[2:3], s[6:7], 0, v[182:183]
	v_lshl_add_u64 v[2:3], v[2:3], 0, s[58:59]
	s_add_i32 m0, s89, 0xe000
	s_nop 0
	global_load_lds_dwordx4 v[2:3], off
	s_waitcnt vmcnt(8)
	s_waitcnt lgkmcnt(0)
	s_barrier
	s_setprio 1
	s_waitcnt lgkmcnt(0)
	v_mfma_f32_16x16x32_bf16 v[124:127], v[132:135], v[164:167], 0
	v_mfma_f32_16x16x32_bf16 v[116:119], v[140:143], v[164:167], 0
	v_mfma_f32_16x16x32_bf16 v[108:111], v[132:135], v[184:187], 0
	v_mfma_f32_16x16x32_bf16 v[100:103], v[140:143], v[184:187], 0
	v_mfma_f32_16x16x32_bf16 v[92:95], v[132:135], v[196:199], 0
	v_mfma_f32_16x16x32_bf16 v[84:87], v[140:143], v[196:199], 0
	v_mfma_f32_16x16x32_bf16 v[76:79], v[132:135], v[210:213], 0
	v_mfma_f32_16x16x32_bf16 v[68:71], v[140:143], v[210:213], 0
	v_mfma_f32_16x16x32_bf16 v[124:127], v[136:139], v[168:171], v[124:127]
	v_mfma_f32_16x16x32_bf16 v[116:119], v[144:147], v[168:171], v[116:119]
	v_mfma_f32_16x16x32_bf16 v[108:111], v[136:139], v[188:191], v[108:111]
	v_mfma_f32_16x16x32_bf16 v[100:103], v[144:147], v[188:191], v[100:103]
	v_mfma_f32_16x16x32_bf16 v[92:95], v[136:139], v[200:203], v[92:95]
	v_mfma_f32_16x16x32_bf16 v[84:87], v[144:147], v[200:203], v[84:87]
	v_mfma_f32_16x16x32_bf16 v[76:79], v[136:139], v[214:217], v[76:79]
	v_mfma_f32_16x16x32_bf16 v[68:71], v[144:147], v[214:217], v[68:71]
	s_setprio 0
	s_setprio 1
	v_mfma_f32_16x16x32_bf16 v[128:131], v[148:151], v[164:167], 0
	v_mfma_f32_16x16x32_bf16 v[120:123], v[156:159], v[164:167], 0
	v_mfma_f32_16x16x32_bf16 v[112:115], v[148:151], v[184:187], 0
	v_mfma_f32_16x16x32_bf16 v[104:107], v[156:159], v[184:187], 0
	v_mfma_f32_16x16x32_bf16 v[96:99], v[148:151], v[196:199], 0
	v_mfma_f32_16x16x32_bf16 v[88:91], v[156:159], v[196:199], 0
	v_mfma_f32_16x16x32_bf16 v[80:83], v[148:151], v[210:213], 0
	v_mfma_f32_16x16x32_bf16 v[72:75], v[156:159], v[210:213], 0
	v_mfma_f32_16x16x32_bf16 v[128:131], v[152:155], v[168:171], v[128:131]
	v_mfma_f32_16x16x32_bf16 v[120:123], v[160:163], v[168:171], v[120:123]
	v_mfma_f32_16x16x32_bf16 v[112:115], v[152:155], v[188:191], v[112:115]
	v_mfma_f32_16x16x32_bf16 v[104:107], v[160:163], v[188:191], v[104:107]
	v_mfma_f32_16x16x32_bf16 v[96:99], v[152:155], v[200:203], v[96:99]
	v_mfma_f32_16x16x32_bf16 v[88:91], v[160:163], v[200:203], v[88:91]
	v_mfma_f32_16x16x32_bf16 v[80:83], v[152:155], v[214:217], v[80:83]
	v_mfma_f32_16x16x32_bf16 v[72:75], v[160:163], v[214:217], v[72:75]
	s_setprio 0
	s_barrier
	s_add_i32 s58, s62, s88
	v_lshl_add_u64 v[192:193], s[60:61], 0, v[178:179]
	s_mov_b32 m0, s58
	ds_read_b128 v[164:167], v208 offset:16384
	ds_read_b128 v[168:171], v208 offset:17408
	ds_read_b128 v[184:187], v208 offset:18432
	ds_read_b128 v[188:191], v208 offset:19456
	ds_read_b128 v[196:199], v208 offset:20480
	ds_read_b128 v[200:203], v208 offset:21504
	ds_read_b128 v[210:213], v208 offset:22528
	ds_read_b128 v[214:217], v208 offset:23552
	global_load_lds_dwordx4 v[192:193], off
	s_add_i32 m0, s58, 0x2000
	s_add_u32 s58, s60, s94
	v_lshl_add_u64 v[204:205], s[60:61], 0, v[174:175]
	s_addc_u32 s59, s61, 0
	s_add_i32 s60, s63, s88
	global_load_lds_dwordx4 v[204:205], off
	v_lshl_add_u64 v[218:219], s[58:59], 0, v[178:179]
	s_mov_b32 m0, s60
	v_lshl_add_u64 v[220:221], s[58:59], 0, v[174:175]
	global_load_lds_dwordx4 v[218:219], off
	s_add_i32 m0, s60, 0x2000
	v_lshl_add_u64 v[2:3], s[8:9], 0, v[176:177]
	global_load_lds_dwordx4 v[220:221], off
	s_mov_b32 m0, s89
	s_nop 0
	global_load_lds_dwordx4 v[2:3], off
	v_lshl_add_u64 v[2:3], s[8:9], 0, v[172:173]
	s_mov_b32 m0, s90
	s_nop 0
	global_load_lds_dwordx4 v[2:3], off
	s_waitcnt vmcnt(8)
	s_waitcnt lgkmcnt(0)
	s_barrier
; #define PG8_STAGE(bufoff, gbase, voff) do { _Pragma("unroll") for (int _i = 0; _i < 2; ++_i) \
;         __builtin_amdgcn_global_load_lds((const unsigned*)((const char*)(gbase) + (voff)[_i]), (PG8_LAS unsigned*)(lds + (bufoff) + ldsw + _i * 8192), 16, 0, 0); } while (0)
; #define PG8_LDA(dst, b, h) do { _Pragma("unroll") for (int m = 0; m < 4; ++m) _Pragma("unroll") for (int k = 0; k < 2; ++k) dst[m][k] = *(const PG8_LAS bf16x8*)(lds + PG8_SA(b, h) + aoff + m * 2048 + k * 1024); } while (0)
; #define PG8_LDB(dst, b, h) do { _Pragma("unroll") for (int n = 0; n < 2; ++n) _Pragma("unroll") for (int k = 0; k < 2; ++k) dst[n][k] = *(const PG8_LAS bf16x8*)(lds + PG8_SB(b, h) + boff + n * 2048 + k * 1024); } while (0)
; #define PG8_MMA(ai, bj, At, Bt) do { __builtin_amdgcn_s_setprio(1); _Pragma("unroll") for (int m = 0; m < 4; ++m) _Pragma("unroll") for (int n = 0; n < 2; ++n) _Pragma("unroll") for (int k = 0; k < 2; ++k) \
;         acc[ai][bj][m][n] = __builtin_amdgcn_mfma_f32_16x16x32_bf16(Bt[n][k], At[m][k], acc[ai][bj][m][n], 0, 0, 0); __builtin_amdgcn_s_setprio(0); } while (0)
; #define PG8_WAIT_V(n) asm volatile("s_waitcnt vmcnt(" #n ")" ::: "memory")
; #define PG8_WAIT_L(n) asm volatile("s_waitcnt lgkmcnt(" #n ")" ::: "memory")
; #define PG8_BAR __builtin_amdgcn_s_barrier()
; #define PG8_SCHED __builtin_amdgcn_sched_barrier(0)
; template <class Epi, class Sched, bool ALIGN_EPI = false, bool SP2 = false>
; __device__ __forceinline__ void gemm_phase(PG8_LAS unsigned char* lds, const Gemm g, const Sched& S, const Epi& E, int tid_in) {
;     ...
;             PG8_WAIT_V(8); PG8_WAIT_L(0); PG8_BAR; PG8_MMA(1, 0, At, B0); PG8_MMA(1, 1, At, B1); PG8_BAR; PG8_SCHED;
;             PG8_LDB(B0, 1, 0); PG8_LDB(B1, 1, 1); PG8_SCHED; PG8_LDA(At, 1, 0); PG8_STAGE(PG8_SA(0, 1), a2 + hstepA, voffA);
;             PG8_WAIT_V(8); PG8_WAIT_L(0); PG8_BAR; PG8_MMA(0, 0, At, B0); PG8_MMA(0, 1, At, B1); PG8_BAR; PG8_SCHED;
	s_setprio 1
	s_waitcnt lgkmcnt(0)
	v_mfma_f32_16x16x32_bf16 v[60:63], v[132:135], v[164:167], 0
	v_mfma_f32_16x16x32_bf16 v[52:55], v[140:143], v[164:167], 0
	v_mfma_f32_16x16x32_bf16 v[44:47], v[132:135], v[184:187], 0
	v_mfma_f32_16x16x32_bf16 v[36:39], v[140:143], v[184:187], 0
	v_mfma_f32_16x16x32_bf16 v[28:31], v[132:135], v[196:199], 0
	v_mfma_f32_16x16x32_bf16 v[20:23], v[140:143], v[196:199], 0
	v_mfma_f32_16x16x32_bf16 v[12:15], v[132:135], v[210:213], 0
	v_mfma_f32_16x16x32_bf16 v[2:5], v[140:143], v[210:213], 0
	v_mfma_f32_16x16x32_bf16 v[60:63], v[136:139], v[168:171], v[60:63]
	v_mfma_f32_16x16x32_bf16 v[52:55], v[144:147], v[168:171], v[52:55]
	v_mfma_f32_16x16x32_bf16 v[44:47], v[136:139], v[188:191], v[44:47]
	v_mfma_f32_16x16x32_bf16 v[36:39], v[144:147], v[188:191], v[36:39]
	v_mfma_f32_16x16x32_bf16 v[28:31], v[136:139], v[200:203], v[28:31]
	v_mfma_f32_16x16x32_bf16 v[20:23], v[144:147], v[200:203], v[20:23]
	v_mfma_f32_16x16x32_bf16 v[12:15], v[136:139], v[214:217], v[12:15]
	v_mfma_f32_16x16x32_bf16 v[2:5], v[144:147], v[214:217], v[2:5]
	s_setprio 0
	s_setprio 1
	v_mfma_f32_16x16x32_bf16 v[64:67], v[148:151], v[164:167], 0
	v_mfma_f32_16x16x32_bf16 v[56:59], v[156:159], v[164:167], 0
	v_mfma_f32_16x16x32_bf16 v[48:51], v[148:151], v[184:187], 0
	v_mfma_f32_16x16x32_bf16 v[40:43], v[156:159], v[184:187], 0
	v_mfma_f32_16x16x32_bf16 v[32:35], v[148:151], v[196:199], 0
	v_mfma_f32_16x16x32_bf16 v[24:27], v[156:159], v[196:199], 0
	v_mfma_f32_16x16x32_bf16 v[16:19], v[148:151], v[210:213], 0
	v_mfma_f32_16x16x32_bf16 v[6:9], v[156:159], v[210:213], 0
	v_mfma_f32_16x16x32_bf16 v[64:67], v[152:155], v[168:171], v[64:67]
	v_mfma_f32_16x16x32_bf16 v[56:59], v[160:163], v[168:171], v[56:59]
	v_mfma_f32_16x16x32_bf16 v[48:51], v[152:155], v[188:191], v[48:51]
	v_mfma_f32_16x16x32_bf16 v[40:43], v[160:163], v[188:191], v[40:43]
	v_mfma_f32_16x16x32_bf16 v[32:35], v[152:155], v[200:203], v[32:35]
	v_mfma_f32_16x16x32_bf16 v[24:27], v[160:163], v[200:203], v[24:27]
	v_mfma_f32_16x16x32_bf16 v[16:19], v[152:155], v[214:217], v[16:19]
	v_mfma_f32_16x16x32_bf16 v[8:11], v[160:163], v[214:217], v[6:9]
	s_setprio 0
	s_barrier
	s_add_i32 s58, 0, 0x18000
	v_add_u32_e32 v0, s58, v207
	s_add_i32 s59, 0, 0x1c000
	ds_read_b128 v[132:135], v0
	ds_read_b128 v[136:139], v0 offset:1024
	ds_read_b128 v[140:143], v0 offset:2048
	ds_read_b128 v[144:147], v0 offset:3072
	v_add_u32_e32 v0, s59, v207
	ds_read_b128 v[148:151], v0
	ds_read_b128 v[152:155], v0 offset:1024
	ds_read_b128 v[156:159], v0 offset:2048
	ds_read_b128 v[160:163], v0 offset:3072
	s_add_u32 s8, s8, s94
	s_addc_u32 s9, s9, 0
	s_mov_b32 m0, s91
	v_lshl_add_u64 v[6:7], s[8:9], 0, v[176:177]
	ds_read_b128 v[164:167], v208 offset:32768
	ds_read_b128 v[168:171], v208 offset:33792
	ds_read_b128 v[184:187], v208 offset:34816
	ds_read_b128 v[188:191], v208 offset:35840
	ds_read_b128 v[196:199], v208 offset:36864
	ds_read_b128 v[200:203], v208 offset:37888
	ds_read_b128 v[210:213], v208 offset:38912
	ds_read_b128 v[214:217], v208 offset:39936
	global_load_lds_dwordx4 v[6:7], off
	v_lshl_add_u64 v[6:7], s[8:9], 0, v[172:173]
	s_mov_b32 m0, s92
	s_nop 0
	global_load_lds_dwordx4 v[6:7], off
	s_waitcnt vmcnt(8)
	s_waitcnt lgkmcnt(0)
	s_barrier
	s_setprio 1
	s_waitcnt lgkmcnt(0)
	v_mfma_f32_16x16x32_bf16 v[124:127], v[132:135], v[164:167], v[124:127]
	v_mfma_f32_16x16x32_bf16 v[116:119], v[140:143], v[164:167], v[116:119]
	v_mfma_f32_16x16x32_bf16 v[108:111], v[132:135], v[184:187], v[108:111]
	v_mfma_f32_16x16x32_bf16 v[100:103], v[140:143], v[184:187], v[100:103]
	v_mfma_f32_16x16x32_bf16 v[92:95], v[132:135], v[196:199], v[92:95]
	v_mfma_f32_16x16x32_bf16 v[84:87], v[140:143], v[196:199], v[84:87]
	v_mfma_f32_16x16x32_bf16 v[76:79], v[132:135], v[210:213], v[76:79]
	v_mfma_f32_16x16x32_bf16 v[68:71], v[140:143], v[210:213], v[68:71]
	v_mfma_f32_16x16x32_bf16 v[124:127], v[136:139], v[168:171], v[124:127]
	v_mfma_f32_16x16x32_bf16 v[116:119], v[144:147], v[168:171], v[116:119]
	v_mfma_f32_16x16x32_bf16 v[108:111], v[136:139], v[188:191], v[108:111]
	v_mfma_f32_16x16x32_bf16 v[100:103], v[144:147], v[188:191], v[100:103]
	v_mfma_f32_16x16x32_bf16 v[92:95], v[136:139], v[200:203], v[92:95]
	v_mfma_f32_16x16x32_bf16 v[84:87], v[144:147], v[200:203], v[84:87]
	v_mfma_f32_16x16x32_bf16 v[76:79], v[136:139], v[214:217], v[76:79]
	v_mfma_f32_16x16x32_bf16 v[68:71], v[144:147], v[214:217], v[68:71]
	s_setprio 0
	s_setprio 1
	v_mfma_f32_16x16x32_bf16 v[128:131], v[148:151], v[164:167], v[128:131]
	v_mfma_f32_16x16x32_bf16 v[120:123], v[156:159], v[164:167], v[120:123]
	v_mfma_f32_16x16x32_bf16 v[112:115], v[148:151], v[184:187], v[112:115]
	v_mfma_f32_16x16x32_bf16 v[104:107], v[156:159], v[184:187], v[104:107]
	v_mfma_f32_16x16x32_bf16 v[96:99], v[148:151], v[196:199], v[96:99]
	v_mfma_f32_16x16x32_bf16 v[88:91], v[156:159], v[196:199], v[88:91]
	v_mfma_f32_16x16x32_bf16 v[80:83], v[148:151], v[210:213], v[80:83]
	v_mfma_f32_16x16x32_bf16 v[72:75], v[156:159], v[210:213], v[72:75]
	v_mfma_f32_16x16x32_bf16 v[128:131], v[152:155], v[168:171], v[128:131]
	v_mfma_f32_16x16x32_bf16 v[120:123], v[160:163], v[168:171], v[120:123]
	v_mfma_f32_16x16x32_bf16 v[112:115], v[152:155], v[188:191], v[112:115]
	v_mfma_f32_16x16x32_bf16 v[104:107], v[160:163], v[188:191], v[104:107]
	v_mfma_f32_16x16x32_bf16 v[96:99], v[152:155], v[200:203], v[96:99]
	v_mfma_f32_16x16x32_bf16 v[88:91], v[160:163], v[200:203], v[88:91]
	v_mfma_f32_16x16x32_bf16 v[80:83], v[152:155], v[214:217], v[80:83]
	v_mfma_f32_16x16x32_bf16 v[72:75], v[160:163], v[214:217], v[72:75]
	s_setprio 0
	s_barrier
; #define PG8_STAGE(bufoff, gbase, voff) do { _Pragma("unroll") for (int _i = 0; _i < 2; ++_i) \
;         __builtin_amdgcn_global_load_lds((const unsigned*)((const char*)(gbase) + (voff)[_i]), (PG8_LAS unsigned*)(lds + (bufoff) + ldsw + _i * 8192), 16, 0, 0); } while (0)
; #define PG8_LDA(dst, b, h) do { _Pragma("unroll") for (int m = 0; m < 4; ++m) _Pragma("unroll") for (int k = 0; k < 2; ++k) dst[m][k] = *(const PG8_LAS bf16x8*)(lds + PG8_SA(b, h) + aoff + m * 2048 + k * 1024); } while (0)
; #define PG8_MMA(ai, bj, At, Bt) do { __builtin_amdgcn_s_setprio(1); _Pragma("unroll") for (int m = 0; m < 4; ++m) _Pragma("unroll") for (int n = 0; n < 2; ++n) _Pragma("unroll") for (int k = 0; k < 2; ++k) \
;         acc[ai][bj][m][n] = __builtin_amdgcn_mfma_f32_16x16x32_bf16(Bt[n][k], At[m][k], acc[ai][bj][m][n], 0, 0, 0); __builtin_amdgcn_s_setprio(0); } while (0)
; #define PG8_WAIT_V(n) asm volatile("s_waitcnt vmcnt(" #n ")" ::: "memory")
; #define PG8_WAIT_L(n) asm volatile("s_waitcnt lgkmcnt(" #n ")" ::: "memory")
; #define PG8_BAR __builtin_amdgcn_s_barrier()
; #define PG8_SCHED __builtin_amdgcn_sched_barrier(0)
; template <class Epi, class Sched, bool ALIGN_EPI = false, bool SP2 = false>
; __device__ __forceinline__ void gemm_phase(PG8_LAS unsigned char* lds, const Gemm g, const Sched& S, const Epi& E, int tid_in) {
;     ...
;             PG8_LDA(At, 1, 1); PG8_STAGE(PG8_SB(1, 0), b3, voffB); PG8_STAGE(PG8_SB(1, 1), b3 + hstep, voffB); PG8_STAGE(PG8_SA(1, 0), a3, voffA);
;             PG8_WAIT_V(8); PG8_WAIT_L(0); PG8_BAR; PG8_MMA(1, 0, At, B0); PG8_MMA(1, 1, At, B1); PG8_BAR; PG8_SCHED;
	s_add_i32 s8, s58, s88
	v_lshl_add_u64 v[6:7], v[192:193], 0, s[96:97]
	s_mov_b32 m0, s8
	ds_read_b128 v[164:167], v208 offset:49152
	ds_read_b128 v[168:171], v208 offset:50176
	ds_read_b128 v[184:187], v208 offset:51200
	ds_read_b128 v[188:191], v208 offset:52224
	ds_read_b128 v[196:199], v208 offset:53248
	ds_read_b128 v[200:203], v208 offset:54272
	ds_read_b128 v[210:213], v208 offset:55296
	ds_read_b128 v[214:217], v208 offset:56320
	global_load_lds_dwordx4 v[6:7], off
	v_lshl_add_u64 v[6:7], v[204:205], 0, s[96:97]
	s_add_i32 m0, s8, 0x2000
	s_add_i32 s8, s59, s88
	global_load_lds_dwordx4 v[6:7], off
	v_lshl_add_u64 v[6:7], v[218:219], 0, s[96:97]
	s_mov_b32 m0, s8
	s_nop 0
	global_load_lds_dwordx4 v[6:7], off
	v_lshl_add_u64 v[6:7], v[220:221], 0, s[96:97]
	s_add_i32 m0, s8, 0x2000
	s_nop 0
	global_load_lds_dwordx4 v[6:7], off
	v_lshl_add_u64 v[6:7], s[0:1], 0, v[176:177]
	s_mov_b32 m0, s93
	s_nop 0
	global_load_lds_dwordx4 v[6:7], off
	v_lshl_add_u64 v[6:7], s[0:1], 0, v[172:173]
	s_mov_b32 m0, s78
	s_nop 0
	global_load_lds_dwordx4 v[6:7], off
	s_waitcnt vmcnt(8)
	s_waitcnt lgkmcnt(0)
	s_barrier
	s_setprio 1
	s_waitcnt lgkmcnt(0)
	v_mfma_f32_16x16x32_bf16 v[60:63], v[132:135], v[164:167], v[60:63]
	v_mfma_f32_16x16x32_bf16 v[52:55], v[140:143], v[164:167], v[52:55]
	v_mfma_f32_16x16x32_bf16 v[44:47], v[132:135], v[184:187], v[44:47]
	v_mfma_f32_16x16x32_bf16 v[36:39], v[140:143], v[184:187], v[36:39]
	v_mfma_f32_16x16x32_bf16 v[28:31], v[132:135], v[196:199], v[28:31]
	v_mfma_f32_16x16x32_bf16 v[20:23], v[140:143], v[196:199], v[20:23]
	v_mfma_f32_16x16x32_bf16 v[12:15], v[132:135], v[210:213], v[12:15]
	v_mfma_f32_16x16x32_bf16 v[2:5], v[140:143], v[210:213], v[2:5]
	v_mfma_f32_16x16x32_bf16 v[60:63], v[136:139], v[168:171], v[60:63]
	v_mfma_f32_16x16x32_bf16 v[52:55], v[144:147], v[168:171], v[52:55]
	v_mfma_f32_16x16x32_bf16 v[44:47], v[136:139], v[188:191], v[44:47]
	v_mfma_f32_16x16x32_bf16 v[36:39], v[144:147], v[188:191], v[36:39]
	v_mfma_f32_16x16x32_bf16 v[28:31], v[136:139], v[200:203], v[28:31]
	v_mfma_f32_16x16x32_bf16 v[20:23], v[144:147], v[200:203], v[20:23]
	v_mfma_f32_16x16x32_bf16 v[12:15], v[136:139], v[214:217], v[12:15]
	v_mfma_f32_16x16x32_bf16 v[4:7], v[144:147], v[214:217], v[2:5]
	s_setprio 0
	s_setprio 1
	v_mfma_f32_16x16x32_bf16 v[64:67], v[148:151], v[164:167], v[64:67]
	v_mfma_f32_16x16x32_bf16 v[56:59], v[156:159], v[164:167], v[56:59]
	v_mfma_f32_16x16x32_bf16 v[48:51], v[148:151], v[184:187], v[48:51]
	v_mfma_f32_16x16x32_bf16 v[40:43], v[156:159], v[184:187], v[40:43]
	v_mfma_f32_16x16x32_bf16 v[32:35], v[148:151], v[196:199], v[32:35]
	v_mfma_f32_16x16x32_bf16 v[24:27], v[156:159], v[196:199], v[24:27]
	v_mfma_f32_16x16x32_bf16 v[16:19], v[148:151], v[210:213], v[16:19]
	v_mfma_f32_16x16x32_bf16 v[8:11], v[156:159], v[210:213], v[8:11]
	v_mfma_f32_16x16x32_bf16 v[64:67], v[152:155], v[168:171], v[64:67]
	v_mfma_f32_16x16x32_bf16 v[56:59], v[160:163], v[168:171], v[56:59]
	v_mfma_f32_16x16x32_bf16 v[48:51], v[152:155], v[188:191], v[48:51]
	v_mfma_f32_16x16x32_bf16 v[40:43], v[160:163], v[188:191], v[40:43]
	v_mfma_f32_16x16x32_bf16 v[32:35], v[152:155], v[200:203], v[32:35]
	v_mfma_f32_16x16x32_bf16 v[24:27], v[160:163], v[200:203], v[24:27]
	v_mfma_f32_16x16x32_bf16 v[16:19], v[152:155], v[214:217], v[16:19]
	v_mfma_f32_16x16x32_bf16 v[8:11], v[160:163], v[214:217], v[8:11]
	s_setprio 0
	s_barrier
	s_add_u32 s6, s6, 0x100
	s_addc_u32 s7, s7, 0
	s_add_u32 s54, s54, 0x100
	s_addc_u32 s55, s55, 0
	s_add_i32 s56, s56, -2
	s_cmp_ge_u32 s57, s18
	s_mov_b32 s0, s57
	s_cbranch_scc1 .Lzk1_exit
